# v13: in-loop grid barriers rewritten: XCD leader publishes its generation flag, all workgroups poll the 8 flags (no top-level counter); on top of v10
# baseline (speedup 1.0000x reference)
; DI unsigned xb_ld(unsigned* p)              { return __hip_atomic_load(p, __ATOMIC_RELAXED, __HIP_MEMORY_SCOPE_AGENT); }
; DI unsigned xb_add(unsigned* p, unsigned v) { return __hip_atomic_fetch_add(p, v, __ATOMIC_RELAXED, __HIP_MEMORY_SCOPE_AGENT); }
; #define XB_SPIN(cond, bar) do { unsigned _sp = 0; while (cond) { \
;     if ((++_sp & 255u) == 0u) { if (xb_ld(&(bar)[XB_TMO])) break; if (_sp > XB_SPIN_CAP) { atomicAdd(&(bar)[XB_TMO], 1u); break; } } } } while (0)
; DI void xcd_barrier(const XcdBarrier& b) {
;     ...
;     if (threadIdx.x == 0) {
;         unsigned* bar = b.bar;
;         __builtin_amdgcn_s_waitcnt(0);
;         unsigned nloc = b.st[0], nx = b.st[1];
;         if (nloc == 0u) { xcd_barrier_complete(bar, b.x, nloc, nx); b.st[0] = nloc; b.st[1] = nx; }
;         const unsigned old = xb_add(&bar[XB_XSUB(b.x)], 1u);
;         const unsigned gen = old / nloc;
;         if (old + 1u == (gen + 1u) * nloc) {
;             __builtin_amdgcn_fence(__ATOMIC_RELEASE, "agent");
;             asm volatile("s_waitcnt vmcnt(0)" ::: "memory");
;             const unsigned og = xb_add(&bar[XB_TOP], 1u);
;             const unsigned tg = og / nx;
;             if (og + 1u == (tg + 1u) * nx) xb_add(&bar[XB_TOPGEN], 1u);
;             else XB_SPIN(xb_ld(&bar[XB_TOPGEN]) == tg, bar);
;             __builtin_amdgcn_fence(__ATOMIC_ACQUIRE, "agent");
;             xb_add(&bar[XB_XGEN(b.x)], 1u);
;             asm volatile("s_waitcnt vmcnt(0)" ::: "memory");
;         } else {
;             XB_SPIN(xb_ld(&bar[XB_XGEN(b.x)]) == gen, bar);
;             __builtin_amdgcn_fence(__ATOMIC_ACQUIRE, "agent");
;             asm volatile("s_waitcnt vmcnt(0)" ::: "memory");
;         }
;     }
;     __syncthreads();
.LBB0_227:
	s_or_b64 exec, exec, s[12:13]
	v_readlane_b32 s4, v254, 4
	v_readlane_b32 s5, v254, 5
	s_barrier
	s_getreg_b32 s0, hwreg(HW_REG_XCC_ID, 0, 4)
	s_waitcnt vmcnt(0)
	s_barrier
	s_mov_b64 s[2:3], exec
	v_readlane_b32 s6, v254, 1
	v_readlane_b32 s7, v254, 2
	s_and_b64 s[6:7], s[2:3], s[6:7]
	s_xor_b64 s[2:3], s[6:7], s[2:3]
	s_mov_b64 exec, s[6:7]
	s_cbranch_execz .LBB0_280
	s_load_dwordx2 s[4:5], s[4:5], 0xd8
	v_mov_b32_e32 v0, 0x23f00
	ds_read_b32 v2, v0
	s_and_b32 s0, s0, 15
	s_lshl_b32 s12, s0, 8
	s_lshl_b32 s14, s0, 2
	v_mov_b32_e32 v3, 1
	v_mov_b32_e32 v1, 0x1000
	s_waitcnt lgkmcnt(0)
	s_add_u32 s6, s4, s12
	s_addc_u32 s7, s5, 0
	global_atomic_add v3, v1, v3, s[6:7] offset:1024 sc0
	v_cvt_f32_u32_e32 v4, v2
	v_sub_u32_e32 v0, 0, v2
	v_rcp_iflag_f32_e32 v4, v4
	s_waitcnt vmcnt(0)
	v_mov_b32_e32 v5, v3
	v_mul_f32_e32 v4, 0x4f7ffffe, v4
	v_cvt_u32_f32_e32 v4, v4
	v_mul_lo_u32 v1, v0, v4
	v_mul_hi_u32 v1, v4, v1
	v_add_u32_e32 v1, v4, v1
	v_mul_hi_u32 v1, v5, v1
	v_mul_lo_u32 v3, v1, v2
	v_sub_u32_e32 v3, v5, v3
	v_add_u32_e32 v4, 1, v1
	v_cmp_ge_u32_e32 vcc, v3, v2
	s_nop 1
	v_cndmask_b32_e32 v1, v1, v4, vcc
	v_sub_u32_e32 v4, v3, v2
	v_cndmask_b32_e32 v3, v3, v4, vcc
	v_add_u32_e32 v4, 1, v1
	v_cmp_ge_u32_e32 vcc, v3, v2
	s_nop 1
	v_cndmask_b32_e32 v1, v1, v4, vcc
	v_mul_lo_u32 v4, v2, v1
	v_add_u32_e32 v4, v4, v2
	v_add_u32_e32 v3, 1, v5
	v_readfirstlane_b32 s10, v1
	v_cmp_ne_u32_e32 vcc, v3, v4
	s_cbranch_vccnz .Lgb0_poll
	buffer_wbl2 sc1
	s_add_i32 s11, s10, 1
	v_mov_b32_e32 v0, s14
	v_mov_b32_e32 v1, s11
	v_add_u32_e32 v0, 0x3800, v0
	s_waitcnt vmcnt(0)
	global_store_dword v0, v1, s[4:5] sc1
.Lgb0_poll:
	s_mov_b32 s11, 0
	v_mov_b32_e32 v0, 0x3800
.Lgb0_spin:
	global_load_dwordx4 v[2:5], v0, s[4:5] sc1
	global_load_dwordx4 v[6:9], v0, s[4:5] offset:16 sc1
	s_waitcnt vmcnt(0)
	v_min3_u32 v1, v2, v3, v4
	v_min3_u32 v2, v5, v6, v7
	v_min3_u32 v1, v1, v8, v9
	v_min_u32_e32 v1, v1, v2
	v_cmp_lt_u32_e32 vcc, s10, v1
	s_cbranch_vccnz .Lgb0_done
	s_add_i32 s11, s11, 1
	s_cmp_lt_u32 s11, 0x10000
	s_cbranch_scc1 .Lgb0_spin
.Lgb0_done:
	buffer_inv sc1
	s_waitcnt vmcnt(0)
	s_branch .LBB0_280
.LBB0_230:
.LBB0_231:
.LBB0_234:
.LBB0_235:
.LBB0_237:
.LBB0_238:
.LBB0_241:
.LBB0_242:
.LBB0_243:
.LBB0_245:
.LBB0_248:
.LBB0_249:
.LBB0_251:
.LBB0_252:
.LBB0_254:
.LBB0_255:
.LBB0_258:
.LBB0_259:
.LBB0_262:
.LBB0_265:
.LBB0_266:
.LBB0_268:
.LBB0_269:
.LBB0_271:
.LBB0_272:
.LBB0_273:
.LBB0_274:
.LBB0_276:
.LBB0_278:
.LBB0_279:
.LBB0_280:
	s_or_b64 exec, exec, s[2:3]
	s_waitcnt lgkmcnt(0)
	s_barrier

; DI unsigned xb_add(unsigned* p, unsigned v) { return __hip_atomic_fetch_add(p, v, __ATOMIC_RELAXED, __HIP_MEMORY_SCOPE_AGENT); }
; DI void xcd_barrier(const XcdBarrier& b) {
;     ...
;     if (threadIdx.x == 0) {
;         unsigned* bar = b.bar;
;         __builtin_amdgcn_s_waitcnt(0);
;         unsigned nloc = b.st[0], nx = b.st[1];
;         if (nloc == 0u) { xcd_barrier_complete(bar, b.x, nloc, nx); b.st[0] = nloc; b.st[1] = nx; }
;         const unsigned old = xb_add(&bar[XB_XSUB(b.x)], 1u);
;         const unsigned gen = old / nloc;
;         if (old + 1u == (gen + 1u) * nloc) {
;             __builtin_amdgcn_fence(__ATOMIC_RELEASE, "agent");
;             asm volatile("s_waitcnt vmcnt(0)" ::: "memory");
;             const unsigned og = xb_add(&bar[XB_TOP], 1u);
;             const unsigned tg = og / nx;
;             if (og + 1u == (tg + 1u) * nx) xb_add(&bar[XB_TOPGEN], 1u);
.LBB0_301:
	v_readlane_b32 s4, v254, 4
	v_readlane_b32 s5, v254, 5
	s_getreg_b32 s0, hwreg(HW_REG_XCC_ID, 0, 4)
	s_waitcnt vmcnt(0)
	s_barrier
	s_mov_b64 s[2:3], exec
	v_readlane_b32 s6, v254, 1
	v_readlane_b32 s7, v254, 2
	s_and_b64 s[6:7], s[2:3], s[6:7]
	s_mov_b64 exec, s[6:7]
	s_cbranch_execz .LBB0_353
	s_load_dwordx2 s[4:5], s[4:5], 0xd8
	v_mov_b32_e32 v0, 0x23f00
	ds_read_b32 v2, v0
	s_and_b32 s0, s0, 15
	s_lshl_b32 s12, s0, 8
	s_lshl_b32 s14, s0, 2
	v_mov_b32_e32 v3, 1
	v_mov_b32_e32 v1, 0x1000
	s_waitcnt lgkmcnt(0)
	s_add_u32 s6, s4, s12
	s_addc_u32 s7, s5, 0
	global_atomic_add v3, v1, v3, s[6:7] offset:1024 sc0
	v_cvt_f32_u32_e32 v4, v2
	v_sub_u32_e32 v0, 0, v2
	v_rcp_iflag_f32_e32 v4, v4
	s_waitcnt vmcnt(0)
	v_mov_b32_e32 v5, v3
	v_mul_f32_e32 v4, 0x4f7ffffe, v4
	v_cvt_u32_f32_e32 v4, v4
	v_mul_lo_u32 v1, v0, v4
	v_mul_hi_u32 v1, v4, v1
	v_add_u32_e32 v1, v4, v1
	v_mul_hi_u32 v1, v5, v1
	v_mul_lo_u32 v3, v1, v2
	v_sub_u32_e32 v3, v5, v3
	v_add_u32_e32 v4, 1, v1
	v_cmp_ge_u32_e32 vcc, v3, v2
	s_nop 1
	v_cndmask_b32_e32 v1, v1, v4, vcc
	v_sub_u32_e32 v4, v3, v2
	v_cndmask_b32_e32 v3, v3, v4, vcc
	v_add_u32_e32 v4, 1, v1
	v_cmp_ge_u32_e32 vcc, v3, v2
	s_nop 1
	v_cndmask_b32_e32 v1, v1, v4, vcc
	v_mul_lo_u32 v4, v2, v1
	v_add_u32_e32 v4, v4, v2
	v_add_u32_e32 v3, 1, v5
	v_readfirstlane_b32 s10, v1
	v_cmp_ne_u32_e32 vcc, v3, v4
	s_cbranch_vccnz .Lgb1_poll
	buffer_wbl2 sc1
	s_add_i32 s11, s10, 1
	v_mov_b32_e32 v0, s14
	v_mov_b32_e32 v1, s11
	v_add_u32_e32 v0, 0x3800, v0
	s_waitcnt vmcnt(0)
	global_store_dword v0, v1, s[4:5] sc1

; #define LAS __attribute__((address_space(3)))
; DI KA get_ka() { KA p = (KA)__builtin_amdgcn_kernarg_segment_ptr(); asm volatile("" : "+s"(p)); return p; }
; DI void run_gemm_res(LAS unsigned char* lds, size_t offA, size_t offB, int K, int ssi, float sc, size_t part_off, unsigned epoch) {
;     const KA a = get_ka(); unsigned char* ws = a->ws;
;     pg8::Gemm g{(const bf16_t*)(ws + offA), (const bf16_t*)(ws + offB), MPAD, DM, K};
;     const pg8::EpiRes E = pg8::EpiRes::make(ws, ssi, sc, part_off, epoch);
;     const int G = gridDim.x, bx = blockIdx.x;
;     if ((G & 7) == 0 && (long)276 * (K / 128) >= (long)G * (K / 128)) {
;         pg8::SKOrder S; S.init(K, G, (bx & 7) * (G >> 3) + (bx >> 3));
.LBB0_304:
.LBB0_305:
.LBB0_308:
.LBB0_309:
.LBB0_311:
.LBB0_312:
.LBB0_315:
.LBB0_316:
.LBB0_317:
.LBB0_319:
.LBB0_322:
.LBB0_323:
.LBB0_325:
.LBB0_326:
.LBB0_328:
.LBB0_329:
.LBB0_332:
.LBB0_333:
.LBB0_336:
.LBB0_339:
.LBB0_340:
.LBB0_342:
.LBB0_343:
.LBB0_345:
.LBB0_346:
.LBB0_347:
.LBB0_348:
.LBB0_350:
.LBB0_352:
.LBB0_353:
	s_or_b64 exec, exec, s[2:3]
	s_xor_b64 s[2:3], s[22:23], -1
	s_waitcnt lgkmcnt(0)
	v_writelane_b32 v255, s2, 4
	s_barrier
	s_nop 0
	v_writelane_b32 v255, s3, 5
	v_readlane_b32 s2, v254, 4
	v_readlane_b32 s3, v254, 5
	s_load_dwordx2 s[10:11], s[2:3], 0xd8
	s_mul_i32 s0, s44, 3
	s_add_i32 s33, s0, 1
	v_writelane_b32 v255, s0, 6
	s_mul_i32 s0, s33, 0x4500
	s_waitcnt lgkmcnt(0)
	s_add_u32 s38, s10, 0x5000000
	s_addc_u32 s39, s11, 0
	s_add_u32 s40, s10, 0xf00000
	s_addc_u32 s41, s11, 0
	s_add_u32 s28, s10, 0x2d00000
	s_addc_u32 s29, s11, 0
	s_lshl_b64 s[2:3], s[0:1], 2
	s_add_u32 s0, s10, s2
	s_addc_u32 s2, s11, s3
	v_readlane_b32 s4, v254, 10
	s_add_u32 s6, s0, 0x100000
	v_readlane_b32 s5, v254, 11
	s_addc_u32 s7, s2, 0
	s_mov_b64 s[2:3], -1
	s_and_b64 vcc, exec, s[4:5]
	s_cbranch_vccz .LBB0_433
	v_readlane_b32 s4, v254, 12
	v_readlane_b32 s20, v254, 22
	v_readlane_b32 s5, v254, 13
	v_readlane_b32 s21, v254, 23
	s_or_b64 s[2:3], s[20:21], s[4:5]
	s_mov_b32 s2, s1
	s_cmp_lg_u64 s[2:3], 0
	s_cbranch_scc0 .LBB0_487
	s_ashr_i32 s2, s5, 31
	s_add_u32 s4, s4, s2
	s_mov_b32 s3, s2
	s_addc_u32 s5, s5, s2
	s_xor_b64 s[4:5], s[4:5], s[2:3]
	v_cvt_f32_u32_e32 v0, s4
	v_cvt_f32_u32_e32 v1, s5
	s_sub_u32 s0, 0, s4
	s_subb_u32 s12, 0, s5
	v_fmac_f32_e32 v0, 0x4f800000, v1
	v_rcp_f32_e32 v0, v0
	s_nop 0
	v_mul_f32_e32 v0, 0x5f7ffffc, v0
	v_mul_f32_e32 v1, 0x2f800000, v0
	v_trunc_f32_e32 v1, v1
	v_fmac_f32_e32 v0, 0xcf800000, v1
	v_cvt_u32_f32_e32 v1, v1
	v_cvt_u32_f32_e32 v0, v0
	v_readfirstlane_b32 s13, v1
	v_readfirstlane_b32 s8, v0
	s_mul_i32 s9, s0, s13
	s_mul_hi_u32 s15, s0, s8
	s_mul_i32 s14, s12, s8
	s_add_i32 s9, s15, s9
	s_add_i32 s9, s9, s14
	s_mul_i32 s16, s0, s8
	s_mul_i32 s15, s8, s9
	s_mul_hi_u32 s17, s8, s16
	s_mul_hi_u32 s14, s8, s9
	s_add_u32 s15, s17, s15
	s_addc_u32 s14, 0, s14
	s_mul_hi_u32 s18, s13, s16
	s_mul_i32 s16, s13, s16
	s_add_u32 s15, s15, s16
	s_mul_hi_u32 s17, s13, s9
	s_addc_u32 s14, s14, s18
	s_addc_u32 s15, s17, 0
	s_mul_i32 s9, s13, s9
	s_add_u32 s9, s14, s9
	s_addc_u32 s14, 0, s15
	s_add_u32 s15, s8, s9
	s_cselect_b64 s[8:9], -1, 0
	s_cmp_lg_u64 s[8:9], 0
	s_addc_u32 s13, s13, s14
	s_mul_i32 s8, s0, s13
	s_mul_hi_u32 s9, s0, s15
	s_add_i32 s8, s9, s8
	s_mul_i32 s12, s12, s15
	s_add_i32 s8, s8, s12
	s_mul_i32 s0, s0, s15
	s_mul_hi_u32 s12, s13, s0
	s_mul_i32 s14, s13, s0
	s_mul_i32 s17, s15, s8
	s_mul_hi_u32 s0, s15, s0
	s_mul_hi_u32 s16, s15, s8
	s_add_u32 s0, s0, s17
	s_addc_u32 s16, 0, s16
	s_add_u32 s0, s0, s14
	s_mul_hi_u32 s9, s13, s8
	s_addc_u32 s0, s16, s12
	s_addc_u32 s9, s9, 0
	s_mul_i32 s8, s13, s8
	s_add_u32 s0, s0, s8
	s_addc_u32 s12, 0, s9
	s_add_u32 s0, s15, s0
	s_cselect_b64 s[8:9], -1, 0
	s_cmp_lg_u64 s[8:9], 0
	s_addc_u32 s14, s13, s12
	s_ashr_i32 s8, s21, 31
	s_add_u32 s12, s20, s8
	s_mov_b32 s9, s8
	s_addc_u32 s13, s21, s8
	s_xor_b64 s[12:13], s[12:13], s[8:9]
	s_mul_i32 s16, s12, s14
	s_mul_hi_u32 s17, s12, s0
	s_mul_hi_u32 s15, s12, s14
	s_add_u32 s16, s17, s16
	s_addc_u32 s15, 0, s15
	s_mul_hi_u32 s18, s13, s0
	s_mul_i32 s0, s13, s0
	s_add_u32 s0, s16, s0
	s_mul_hi_u32 s17, s13, s14
	s_addc_u32 s0, s15, s18
	s_addc_u32 s15, s17, 0
	s_mul_i32 s14, s13, s14
	s_add_u32 s0, s0, s14
	s_addc_u32 s18, 0, s15
	s_mul_i32 s14, s4, s18
	s_mul_hi_u32 s15, s4, s0
	s_add_i32 s14, s15, s14
	s_mul_i32 s15, s5, s0
	s_add_i32 s19, s14, s15
	s_sub_i32 s16, s13, s19
	s_mul_i32 s14, s4, s0
	s_sub_u32 s12, s12, s14
	s_cselect_b64 s[14:15], -1, 0
	s_cmp_lg_u64 s[14:15], 0
	s_subb_u32 s20, s16, s5
	s_sub_u32 s21, s12, s4
	s_cselect_b64 s[16:17], -1, 0
	s_cmp_lg_u64 s[16:17], 0
	s_subb_u32 s16, s20, 0
	s_cmp_ge_u32 s16, s5
	s_cselect_b32 s17, -1, 0
	s_cmp_ge_u32 s21, s4
	s_cselect_b32 s20, -1, 0
	s_cmp_eq_u32 s16, s5
	s_cselect_b32 s16, s20, s17
	s_add_u32 s17, s0, 1
	s_addc_u32 s20, s18, 0
	s_add_u32 s21, s0, 2
	s_addc_u32 s22, s18, 0
	s_cmp_lg_u32 s16, 0
	s_cselect_b32 s16, s21, s17
	s_cselect_b32 s17, s22, s20
	s_cmp_lg_u64 s[14:15], 0
	s_subb_u32 s13, s13, s19
	s_cmp_ge_u32 s13, s5
	s_cselect_b32 s14, -1, 0
	s_cmp_ge_u32 s12, s4
	s_cselect_b32 s4, -1, 0
	s_cmp_eq_u32 s13, s5
	s_cselect_b32 s4, s4, s14
	s_cmp_lg_u32 s4, 0
	s_cselect_b32 s5, s17, s18
	s_cselect_b32 s4, s16, s0
	s_xor_b64 s[2:3], s[8:9], s[2:3]
	s_xor_b64 s[4:5], s[4:5], s[2:3]
	s_sub_u32 s2, s4, s2
	s_cbranch_execnz .LBB0_357

; DI unsigned xb_add(unsigned* p, unsigned v) { return __hip_atomic_fetch_add(p, v, __ATOMIC_RELAXED, __HIP_MEMORY_SCOPE_AGENT); }
; DI void xcd_barrier(const XcdBarrier& b) {
;     ...
;     if (threadIdx.x == 0) {
;         unsigned* bar = b.bar;
;         __builtin_amdgcn_s_waitcnt(0);
;         unsigned nloc = b.st[0], nx = b.st[1];
;         if (nloc == 0u) { xcd_barrier_complete(bar, b.x, nloc, nx); b.st[0] = nloc; b.st[1] = nx; }
;         const unsigned old = xb_add(&bar[XB_XSUB(b.x)], 1u);
;         const unsigned gen = old / nloc;
;         if (old + 1u == (gen + 1u) * nloc) {
;             __builtin_amdgcn_fence(__ATOMIC_RELEASE, "agent");
;             asm volatile("s_waitcnt vmcnt(0)" ::: "memory");
;             const unsigned og = xb_add(&bar[XB_TOP], 1u);
;             const unsigned tg = og / nx;
;             if (og + 1u == (tg + 1u) * nx) xb_add(&bar[XB_TOPGEN], 1u);
.LBB0_476:
	v_readlane_b32 s4, v254, 4
	v_readlane_b32 s5, v254, 5
	s_getreg_b32 s0, hwreg(HW_REG_XCC_ID, 0, 4)
	s_waitcnt vmcnt(0)
	s_waitcnt vmcnt(0) lgkmcnt(0)
	s_barrier
	s_mov_b64 s[2:3], exec
	v_readlane_b32 s6, v254, 1
	v_readlane_b32 s7, v254, 2
	s_and_b64 s[6:7], s[2:3], s[6:7]
	s_mov_b64 exec, s[6:7]
	s_cbranch_execz .LBB0_530
	s_load_dwordx2 s[4:5], s[4:5], 0xd8
	v_mov_b32_e32 v0, 0x23f00
	ds_read_b32 v2, v0
	s_and_b32 s0, s0, 15
	s_lshl_b32 s12, s0, 8
	s_lshl_b32 s14, s0, 2
	v_mov_b32_e32 v3, 1
	v_mov_b32_e32 v1, 0x1000
	s_waitcnt lgkmcnt(0)
	s_add_u32 s6, s4, s12
	s_addc_u32 s7, s5, 0
	global_atomic_add v3, v1, v3, s[6:7] offset:1024 sc0
	v_cvt_f32_u32_e32 v4, v2
	v_sub_u32_e32 v0, 0, v2
	v_rcp_iflag_f32_e32 v4, v4
	s_waitcnt vmcnt(0)
	v_mov_b32_e32 v5, v3
	v_mul_f32_e32 v4, 0x4f7ffffe, v4
	v_cvt_u32_f32_e32 v4, v4
	v_mul_lo_u32 v1, v0, v4
	v_mul_hi_u32 v1, v4, v1
	v_add_u32_e32 v1, v4, v1
	v_mul_hi_u32 v1, v5, v1
	v_mul_lo_u32 v3, v1, v2
	v_sub_u32_e32 v3, v5, v3
	v_add_u32_e32 v4, 1, v1
	v_cmp_ge_u32_e32 vcc, v3, v2
	s_nop 1
	v_cndmask_b32_e32 v1, v1, v4, vcc
	v_sub_u32_e32 v4, v3, v2
	v_cndmask_b32_e32 v3, v3, v4, vcc
	v_add_u32_e32 v4, 1, v1
	v_cmp_ge_u32_e32 vcc, v3, v2
	s_nop 1
	v_cndmask_b32_e32 v1, v1, v4, vcc
	v_mul_lo_u32 v4, v2, v1
	v_add_u32_e32 v4, v4, v2
	v_add_u32_e32 v3, 1, v5
	v_readfirstlane_b32 s10, v1
	v_cmp_ne_u32_e32 vcc, v3, v4
	s_cbranch_vccnz .Lgb2_poll
	buffer_wbl2 sc1
	s_add_i32 s11, s10, 1
	v_mov_b32_e32 v0, s14
	v_mov_b32_e32 v1, s11
	v_add_u32_e32 v0, 0x3800, v0
	s_waitcnt vmcnt(0)
	global_store_dword v0, v1, s[4:5] sc1

; DI unsigned xb_ld(unsigned* p)              { return __hip_atomic_load(p, __ATOMIC_RELAXED, __HIP_MEMORY_SCOPE_AGENT); }
; DI unsigned xb_add(unsigned* p, unsigned v) { return __hip_atomic_fetch_add(p, v, __ATOMIC_RELAXED, __HIP_MEMORY_SCOPE_AGENT); }
; #define XB_SPIN(cond, bar) do { unsigned _sp = 0; while (cond) { \
;     if ((++_sp & 255u) == 0u) { if (xb_ld(&(bar)[XB_TMO])) break; if (_sp > XB_SPIN_CAP) { atomicAdd(&(bar)[XB_TMO], 1u); break; } } } } while (0)
; DI void xcd_barrier(const XcdBarrier& b) {
;     ...
;             else XB_SPIN(xb_ld(&bar[XB_TOPGEN]) == tg, bar);
;             __builtin_amdgcn_fence(__ATOMIC_ACQUIRE, "agent");
;             xb_add(&bar[XB_XGEN(b.x)], 1u);
;             asm volatile("s_waitcnt vmcnt(0)" ::: "memory");
;         } else {
;             XB_SPIN(xb_ld(&bar[XB_XGEN(b.x)]) == gen, bar);
;             __builtin_amdgcn_fence(__ATOMIC_ACQUIRE, "agent");
;             asm volatile("s_waitcnt vmcnt(0)" ::: "memory");
;         }
.LBB0_479:
.LBB0_480:
.LBB0_483:
.LBB0_484:
.LBB0_486:
.LBB0_487:
	s_branch .LBB0_356

; #define PG8_STAGE(bufoff, gbase, voff) do { _Pragma("unroll") for (int _i = 0; _i < 2; ++_i) \
;         __builtin_amdgcn_global_load_lds((const unsigned*)((const char*)(gbase) + (voff)[_i]), (PG8_LAS unsigned*)(lds + (bufoff) + ldsw + _i * 8192), 16, 0, 0); } while (0)
; #define PG8_BAR __builtin_amdgcn_s_barrier()
; template <class Epi, class Sched, bool ALIGN_EPI = false, bool SP2 = false>
; __device__ __forceinline__ void gemm_phase(PG8_LAS unsigned char* lds, const Gemm g, const Sched& S, const Epi& E) {
;     ...
;     for (int i = 0; i < 2; ++i) { int R, C; stage_rc(tid * 16 + i * 8192, R, C); const int Rb = Epi::PERM ? ((R & ~31) + perm32(R & 31)) : R;
;         voffA[i] = (unsigned)(R * K + C) * 2u; voffB[i] = (unsigned)(Rb * K + C) * 2u; }
;     const size_t kstep = (size_t)(BK * 2);
;     const size_t hstep = (size_t)HALF * K * 2;
;     const size_t tstep = 2 * hstep;
;     const unsigned ldsw = (unsigned)wid * 1024u;
;     const int aoff = lds_byte(wr * 64 + fr, fq * 8), boff = lds_byte(wc * 32 + fr, fq * 8);
;     ...
;     Unit cur, nxt; int ui = 0;
;     if (!S.next(0, cur)) return;
;     f32x4 acc[2][2][4][2];
; #pragma unroll
;     for (int a = 0; a < 2; ++a)
; #pragma unroll
;         for (int b = 0; b < 2; ++b)
; #pragma unroll
;             for (int m = 0; m < 4; ++m)
; #pragma unroll
;                 for (int n = 0; n < 2; ++n) acc[a][b][m][n] = (f32x4){0.f, 0.f, 0.f, 0.f};
;     bf16x8 At[4][2], B0[2][2], B1[2][2];
;     const char* cA = (const char*)g.A + (size_t)cur.pm * tstep + (size_t)cur.kt0 * kstep; const char* cB = (const char*)g.Bt + (size_t)cur.pn * tstep + (size_t)cur.kt0 * kstep;
;     S.a_ready(cur);
;     if constexpr (SP2) {
;         PG8_STAGE(PG8_SB(0, 0), cB, voffB); PG8_STAGE(PG8_SB(0, 1), cB + hstep, voffB); PG8_STAGE(PG8_SA(0, 0), cA, voffA); PG8_STAGE(PG8_SA(0, 1), cA + hstep, voffA);
;         if (wr == 1) PG8_BAR;
.LBB0_489:
.LBB0_492:
.LBB0_493:
.LBB0_494:
.LBB0_496:
.LBB0_499:
.LBB0_500:
.LBB0_502:
.LBB0_503:
.LBB0_505:
.LBB0_506:
.LBB0_509:
.LBB0_510:
.LBB0_513:
.LBB0_516:
.LBB0_517:
.LBB0_519:
.LBB0_520:
.LBB0_522:
.LBB0_523:
.LBB0_524:
.LBB0_525:
.LBB0_527:
.LBB0_529:
.LBB0_530:
	s_or_b64 exec, exec, s[2:3]
	v_readlane_b32 s2, v254, 4
	v_readlane_b32 s4, v254, 16
	v_readlane_b32 s3, v254, 5
	v_mov_b32_e32 v8, v212
	v_readlane_b32 s5, v254, 17
	s_waitcnt lgkmcnt(0)
	s_barrier
	s_andn2_b64 vcc, exec, s[4:5]
	v_readfirstlane_b32 s6, v8
	s_cbranch_vccnz .LBB0_546
	v_lshlrev_b32_e32 v0, 4, v8
	v_add_u32_e32 v1, 0x2000, v0
	v_ashrrev_i32_e32 v2, 31, v1
	v_lshrrev_b32_e32 v2, 22, v2
	v_add_u32_e32 v2, v1, v2
	v_ashrrev_i32_e32 v9, 10, v2
	v_mul_i32_i24_e32 v2, 0x400, v9
	v_sub_u32_e32 v1, v1, v2
	v_lshrrev_b32_e32 v2, 4, v1
	v_bitop3_b32 v1, v2, v1, 32 bitop3:0x6c
	v_ashrrev_i32_e32 v2, 31, v1
	v_lshrrev_b32_e32 v2, 26, v2
	v_add_u32_e32 v2, v1, v2
	v_lshlrev_b32_e32 v3, 3, v9
	v_ashrrev_i32_e32 v10, 6, v2
	v_and_b32_e32 v3, -16, v3
	v_add_u32_e32 v3, v10, v3
	s_load_dwordx2 s[4:5], s[2:3], 0xd8
	v_and_b32_e32 v4, 3, v10
	s_mov_b32 s2, 0x1fffe0
	v_lshrrev_b32_e32 v5, 2, v3
	v_lshlrev_b32_e32 v6, 1, v3
	v_and_b32_e32 v2, 0xc0, v2
	v_and_or_b32 v4, v3, s2, v4
	v_and_b32_e32 v5, 4, v5
	v_and_b32_e32 v6, 24, v6
	v_sub_u32_e32 v1, v1, v2
	v_or3_b32 v4, v4, v5, v6
	v_lshlrev_b32_e32 v5, 5, v9
	v_ashrrev_i16_sdwa v1, v216, sext(v1) dst_sel:DWORD dst_unused:UNUSED_PAD src0_sel:DWORD src1_sel:BYTE_0
	v_and_b32_e32 v5, 32, v5
	v_bfe_i32 v11, v1, 0, 16
	v_add_lshl_u32 v1, v5, v11, 1
	v_lshl_add_u32 v128, v4, 11, v1
	v_lshl_add_u32 v130, v3, 11, v1
	v_bfe_i32 v1, v8, 27, 1
	v_lshrrev_b32_e32 v1, 22, v1
	v_add_u32_e32 v1, v0, v1
	v_and_b32_e32 v1, 0xfffffc00, v1
	v_sub_u32_e32 v0, v0, v1
	v_lshrrev_b32_e32 v1, 4, v0
	v_ashrrev_i32_e32 v2, 31, v8
	v_bitop3_b32 v0, v1, v0, 32 bitop3:0x6c
	v_lshrrev_b32_e32 v2, 26, v2
	v_ashrrev_i32_e32 v1, 31, v0
	v_add_u32_e32 v2, v8, v2
	v_lshrrev_b32_e32 v1, 26, v1
	v_ashrrev_i32_e32 v13, 6, v2
	v_add_u32_e32 v1, v0, v1
	v_lshlrev_b32_e32 v2, 3, v13
	s_waitcnt lgkmcnt(0)
	s_add_u32 s0, s4, 0x2d00000
	v_ashrrev_i32_e32 v12, 6, v1
	v_and_b32_e32 v2, -16, v2
	s_addc_u32 s26, s5, 0
	v_add_u32_e32 v2, v12, v2
	s_add_u32 s27, s4, 0x1480000
	v_and_b32_e32 v3, 3, v12
	v_lshrrev_b32_e32 v4, 2, v2
	v_lshlrev_b32_e32 v5, 1, v2
	v_and_b32_e32 v1, 0xc0, v1
	s_addc_u32 s28, s5, 0
	s_ashr_i32 s8, s6, 6
	v_and_or_b32 v3, v2, s2, v3
	v_and_b32_e32 v4, 4, v4
	v_and_b32_e32 v5, 24, v5
	v_sub_u32_e32 v0, v0, v1
	s_ashr_i32 s7, s6, 8
	s_lshl_b32 s29, s8, 10
	v_or3_b32 v3, v3, v4, v5
	v_lshlrev_b32_e32 v4, 5, v13
	v_ashrrev_i16_sdwa v0, v216, sext(v0) dst_sel:DWORD dst_unused:UNUSED_PAD src0_sel:DWORD src1_sel:BYTE_0
	v_readlane_b32 s2, v254, 41
	v_and_b32_e32 v4, 32, v4
	v_bfe_i32 v14, v0, 0, 16
	v_readlane_b32 s3, v254, 42
	s_add_u32 s20, s27, s2
	v_add_lshl_u32 v0, v4, v14, 1
	s_addc_u32 s21, s28, s3
	s_add_i32 s30, s29, 0
	v_lshl_add_u32 v144, v3, 11, v0
	s_add_i32 m0, s30, 0x10000
	v_lshl_add_u32 v132, v2, 11, v0
	global_load_lds_dwordx4 v144, s[20:21]
	s_add_i32 m0, s30, 0x12000
	s_add_u32 s2, s20, 0x40000
	global_load_lds_dwordx4 v128, s[20:21]
	s_addc_u32 s3, s21, 0
	s_add_i32 m0, s30, 0x14000
	v_mov_b32_e32 v129, v145
	global_load_lds_dwordx4 v144, s[2:3]
	s_add_i32 m0, s30, 0x16000
	v_mov_b32_e32 v133, v145
	global_load_lds_dwordx4 v128, s[2:3]
	v_readlane_b32 s2, v254, 52
	v_readlane_b32 s3, v254, 53
	s_add_u32 s22, s0, s2
	s_addc_u32 s23, s26, s3
	s_add_i32 s31, s30, 0x2000
	s_mov_b32 m0, s30
	s_add_u32 s2, s22, 0x40000
	global_load_lds_dwordx4 v132, s[22:23]
	s_mov_b32 m0, s31
	s_addc_u32 s3, s23, 0
	s_add_i32 s34, s30, 0x4000
	global_load_lds_dwordx4 v130, s[22:23]
	s_mov_b32 m0, s34
	s_add_i32 s35, s30, 0x6000
	global_load_lds_dwordx4 v132, s[2:3]
	s_mov_b32 m0, s35
	v_mov_b32_e32 v131, v145
	global_load_lds_dwordx4 v130, s[2:3]
	s_cmp_eq_u32 s7, 1
	v_lshl_add_u64 v[6:7], s[20:21], 0, v[144:145]
	v_lshl_add_u64 v[4:5], s[20:21], 0, v[128:129]
	v_lshl_add_u64 v[0:1], s[22:23], 0, v[132:133]
	s_cselect_b64 s[18:19], -1, 0
	s_cmp_lg_u32 s7, 1
	v_lshl_add_u64 v[2:3], s[22:23], 0, v[130:131]
	s_cbranch_scc1 .LBB0_533
	s_barrier

; DI unsigned xb_ld(unsigned* p)              { return __hip_atomic_load(p, __ATOMIC_RELAXED, __HIP_MEMORY_SCOPE_AGENT); }
; DI unsigned xb_add(unsigned* p, unsigned v) { return __hip_atomic_fetch_add(p, v, __ATOMIC_RELAXED, __HIP_MEMORY_SCOPE_AGENT); }
; #define XB_SPIN(cond, bar) do { unsigned _sp = 0; while (cond) { \
;     if ((++_sp & 255u) == 0u) { if (xb_ld(&(bar)[XB_TMO])) break; if (_sp > XB_SPIN_CAP) { atomicAdd(&(bar)[XB_TMO], 1u); break; } } } } while (0)
; DI void xcd_barrier(const XcdBarrier& b) {
;     ...
;     if (threadIdx.x == 0) {
;         unsigned* bar = b.bar;
;         __builtin_amdgcn_s_waitcnt(0);
;         unsigned nloc = b.st[0], nx = b.st[1];
;         if (nloc == 0u) { xcd_barrier_complete(bar, b.x, nloc, nx); b.st[0] = nloc; b.st[1] = nx; }
;         const unsigned old = xb_add(&bar[XB_XSUB(b.x)], 1u);
;         const unsigned gen = old / nloc;
;         if (old + 1u == (gen + 1u) * nloc) {
;             __builtin_amdgcn_fence(__ATOMIC_RELEASE, "agent");
;             asm volatile("s_waitcnt vmcnt(0)" ::: "memory");
;             const unsigned og = xb_add(&bar[XB_TOP], 1u);
;             const unsigned tg = og / nx;
;             if (og + 1u == (tg + 1u) * nx) xb_add(&bar[XB_TOPGEN], 1u);
;             else XB_SPIN(xb_ld(&bar[XB_TOPGEN]) == tg, bar);
;             __builtin_amdgcn_fence(__ATOMIC_ACQUIRE, "agent");
;             xb_add(&bar[XB_XGEN(b.x)], 1u);
;             asm volatile("s_waitcnt vmcnt(0)" ::: "memory");
;         } else {
;             XB_SPIN(xb_ld(&bar[XB_XGEN(b.x)]) == gen, bar);
;             __builtin_amdgcn_fence(__ATOMIC_ACQUIRE, "agent");
;             asm volatile("s_waitcnt vmcnt(0)" ::: "memory");
;         }
.LBB0_549:
.LBB0_550:
.LBB0_553:
.LBB0_554:
.LBB0_556:
.LBB0_557:
.LBB0_560:
.LBB0_561:
.LBB0_562:
.LBB0_564:
.LBB0_567:
.LBB0_568:
.LBB0_570:
.LBB0_571:
.LBB0_573:
.LBB0_574:
.LBB0_577:
.LBB0_578:
.LBB0_581:
.LBB0_584:
.LBB0_585:
.LBB0_587:
.LBB0_588:
.LBB0_590:
.LBB0_591:
.LBB0_592:
.LBB0_593:
.LBB0_595:
.LBB0_597:
.LBB0_598:
	s_or_b64 exec, exec, s[2:3]
	s_lshl_b32 s0, s44, 9
	v_writelane_b32 v255, s0, 0
	s_lshl_b32 s2, s44, 12
	s_mov_b32 s3, s1
	v_writelane_b32 v255, s2, 1
	s_lshl_b32 s0, s44, 8
	v_readlane_b32 s33, v254, 0
	v_writelane_b32 v255, s3, 2
	v_readlane_b32 s2, v254, 18
	v_readlane_b32 s3, v254, 19
	v_writelane_b32 v255, s0, 3
	s_andn2_b64 vcc, exec, s[2:3]
	s_waitcnt lgkmcnt(0)
	s_barrier
	s_cbranch_vccz .LBB0_603
.LBB0_599:
	v_readlane_b32 s4, v254, 4
	v_readlane_b32 s5, v254, 5
	s_getreg_b32 s0, hwreg(HW_REG_XCC_ID, 0, 4)
	s_waitcnt vmcnt(0)
	s_waitcnt vmcnt(63) expcnt(7) lgkmcnt(15)
	s_barrier
	s_mov_b64 s[2:3], exec
	v_readlane_b32 s6, v254, 1
	v_readlane_b32 s7, v254, 2
	s_and_b64 s[6:7], s[2:3], s[6:7]
	s_mov_b64 exec, s[6:7]
	s_cbranch_execz .LBB0_728
	s_load_dwordx2 s[4:5], s[4:5], 0xd8
	v_mov_b32_e32 v0, 0x23f00
	ds_read_b32 v2, v0
	s_and_b32 s0, s0, 15
	s_lshl_b32 s12, s0, 8
	s_lshl_b32 s14, s0, 2
	v_mov_b32_e32 v3, 1
	v_mov_b32_e32 v1, 0x1000
	s_waitcnt lgkmcnt(0)
	s_add_u32 s6, s4, s12
	s_addc_u32 s7, s5, 0
	global_atomic_add v3, v1, v3, s[6:7] offset:1024 sc0
	v_cvt_f32_u32_e32 v4, v2
	v_sub_u32_e32 v0, 0, v2
	v_rcp_iflag_f32_e32 v4, v4
	s_waitcnt vmcnt(0)
	v_mov_b32_e32 v5, v3
	v_mul_f32_e32 v4, 0x4f7ffffe, v4
	v_cvt_u32_f32_e32 v4, v4
	v_mul_lo_u32 v1, v0, v4
	v_mul_hi_u32 v1, v4, v1
	v_add_u32_e32 v1, v4, v1
	v_mul_hi_u32 v1, v5, v1
	v_mul_lo_u32 v3, v1, v2
	v_sub_u32_e32 v3, v5, v3
	v_add_u32_e32 v4, 1, v1
	v_cmp_ge_u32_e32 vcc, v3, v2
	s_nop 1
	v_cndmask_b32_e32 v1, v1, v4, vcc
	v_sub_u32_e32 v4, v3, v2
	v_cndmask_b32_e32 v3, v3, v4, vcc
	v_add_u32_e32 v4, 1, v1
	v_cmp_ge_u32_e32 vcc, v3, v2
	s_nop 1
	v_cndmask_b32_e32 v1, v1, v4, vcc
	v_mul_lo_u32 v4, v2, v1
	v_add_u32_e32 v4, v4, v2
	v_add_u32_e32 v3, 1, v5
	v_readfirstlane_b32 s10, v1
	v_cmp_ne_u32_e32 vcc, v3, v4
	s_cbranch_vccnz .Lgb4_poll
	buffer_wbl2 sc1
	s_add_i32 s11, s10, 1
	v_mov_b32_e32 v0, s14
	v_mov_b32_e32 v1, s11
	v_add_u32_e32 v0, 0x3800, v0
	s_waitcnt vmcnt(0)
	global_store_dword v0, v1, s[4:5] sc1

; DI int opaque_tid() { int t = threadIdx.x; asm volatile("" : "+v"(t)); return t; }
; DI void state_scan(KA a, int l) {
;     const int gt = blockIdx.x * 512 + opaque_tid(), NGT = gridDim.x * 512;
;     float* SB = (float*)(a->ws + WS_SB); const float* db = (const float*)(a->ws + WS_DBUF);
;     bf16_t* SBh = (bf16_t*)SB;
;     for (int q = gt; q < NB * NH * 1024; q += NGT) {
;         const int e = (q & 1023) * 8, bh = q >> 10, b = bh >> 2, hd = bh & 3, dkk = e >> 7;
.LBB0_679:
.LBB0_680:
.LBB0_683:
.LBB0_684:
.LBB0_686:
.LBB0_687:
.LBB0_690:
.LBB0_691:
.LBB0_692:
.LBB0_694:
.LBB0_697:
.LBB0_698:
.LBB0_700:
.LBB0_701:
.LBB0_703:
.LBB0_704:
.LBB0_707:
.LBB0_708:
.LBB0_711:
.LBB0_714:
.LBB0_715:
.LBB0_717:
.LBB0_718:
.LBB0_720:
.LBB0_721:
.LBB0_722:
.LBB0_723:
.LBB0_725:
.LBB0_727:
.LBB0_728:
	s_or_b64 exec, exec, s[2:3]
	v_readlane_b32 s2, v254, 4
	v_readlane_b32 s3, v254, 5
	s_waitcnt lgkmcnt(0)
	v_mov_b32_e32 v0, v212
	s_barrier
	s_load_dwordx2 s[12:13], s[2:3], 0xd8
	v_readlane_b32 s0, v254, 3
	s_nop 1
	v_add_u32_e32 v8, s0, v0
	s_mov_b32 s0, 0x8000
	v_cmp_gt_i32_e32 vcc, s0, v8
	s_and_saveexec_b64 s[4:5], vcc
	s_cbranch_execz .LBB0_733
	s_waitcnt lgkmcnt(0)
	s_add_u32 s6, s12, 0xd200000
	s_addc_u32 s7, s13, 0
	s_add_u32 s8, s12, 0x380000
	s_addc_u32 s9, s13, 0
	s_lshl_b32 s0, s44, 5
	s_mov_b64 s[10:11], 0
	v_mov_b32_e32 v9, v8

; DI unsigned xb_ld(unsigned* p)              { return __hip_atomic_load(p, __ATOMIC_RELAXED, __HIP_MEMORY_SCOPE_AGENT); }
; DI unsigned xb_add(unsigned* p, unsigned v) { return __hip_atomic_fetch_add(p, v, __ATOMIC_RELAXED, __HIP_MEMORY_SCOPE_AGENT); }
; #define XB_SPIN(cond, bar) do { unsigned _sp = 0; while (cond) { \
;     if ((++_sp & 255u) == 0u) { if (xb_ld(&(bar)[XB_TMO])) break; if (_sp > XB_SPIN_CAP) { atomicAdd(&(bar)[XB_TMO], 1u); break; } } } } while (0)
; DI void xcd_barrier(const XcdBarrier& b) {
;     asm volatile("s_waitcnt vmcnt(0)" ::: "memory");
;     __syncthreads();
;     if (threadIdx.x == 0) {
;         unsigned* bar = b.bar;
;         __builtin_amdgcn_s_waitcnt(0);
;         unsigned nloc = b.st[0], nx = b.st[1];
;         if (nloc == 0u) { xcd_barrier_complete(bar, b.x, nloc, nx); b.st[0] = nloc; b.st[1] = nx; }
;         const unsigned old = xb_add(&bar[XB_XSUB(b.x)], 1u);
;         const unsigned gen = old / nloc;
;         if (old + 1u == (gen + 1u) * nloc) {
;             __builtin_amdgcn_fence(__ATOMIC_RELEASE, "agent");
;             asm volatile("s_waitcnt vmcnt(0)" ::: "memory");
;             const unsigned og = xb_add(&bar[XB_TOP], 1u);
;             const unsigned tg = og / nx;
;             if (og + 1u == (tg + 1u) * nx) xb_add(&bar[XB_TOPGEN], 1u);
;             else XB_SPIN(xb_ld(&bar[XB_TOPGEN]) == tg, bar);
;             __builtin_amdgcn_fence(__ATOMIC_ACQUIRE, "agent");
;             xb_add(&bar[XB_XGEN(b.x)], 1u);
;             asm volatile("s_waitcnt vmcnt(0)" ::: "memory");
;         } else {
;             XB_SPIN(xb_ld(&bar[XB_XGEN(b.x)]) == gen, bar);
;             __builtin_amdgcn_fence(__ATOMIC_ACQUIRE, "agent");
;             asm volatile("s_waitcnt vmcnt(0)" ::: "memory");
;         }
;     }
;     __syncthreads();
; }
.LBB0_736:
	s_or_b64 exec, exec, s[2:3]
	v_readlane_b32 s4, v254, 4
	v_readlane_b32 s5, v254, 5
	s_getreg_b32 s0, hwreg(HW_REG_XCC_ID, 0, 4)
	s_waitcnt vmcnt(0)
	s_waitcnt lgkmcnt(0)
	s_barrier
	s_mov_b64 s[2:3], exec
	v_readlane_b32 s6, v254, 1
	v_readlane_b32 s7, v254, 2
	s_and_b64 s[6:7], s[2:3], s[6:7]
	s_mov_b64 exec, s[6:7]
	s_cbranch_execz .LBB0_788
	s_load_dwordx2 s[4:5], s[4:5], 0xd8
	v_mov_b32_e32 v0, 0x23f00
	ds_read_b32 v2, v0
	s_and_b32 s0, s0, 15
	s_lshl_b32 s12, s0, 8
	s_lshl_b32 s14, s0, 2
	v_mov_b32_e32 v3, 1
	v_mov_b32_e32 v1, 0x1000
	s_waitcnt lgkmcnt(0)
	s_add_u32 s6, s4, s12
	s_addc_u32 s7, s5, 0
	global_atomic_add v3, v1, v3, s[6:7] offset:1024 sc0
	v_cvt_f32_u32_e32 v4, v2
	v_sub_u32_e32 v0, 0, v2
	v_rcp_iflag_f32_e32 v4, v4
	s_waitcnt vmcnt(0)
	v_mov_b32_e32 v5, v3
	v_mul_f32_e32 v4, 0x4f7ffffe, v4
	v_cvt_u32_f32_e32 v4, v4
	v_mul_lo_u32 v1, v0, v4
	v_mul_hi_u32 v1, v4, v1
	v_add_u32_e32 v1, v4, v1
	v_mul_hi_u32 v1, v5, v1
	v_mul_lo_u32 v3, v1, v2
	v_sub_u32_e32 v3, v5, v3
	v_add_u32_e32 v4, 1, v1
	v_cmp_ge_u32_e32 vcc, v3, v2
	s_nop 1
	v_cndmask_b32_e32 v1, v1, v4, vcc
	v_sub_u32_e32 v4, v3, v2
	v_cndmask_b32_e32 v3, v3, v4, vcc
	v_add_u32_e32 v4, 1, v1
	v_cmp_ge_u32_e32 vcc, v3, v2
	s_nop 1
	v_cndmask_b32_e32 v1, v1, v4, vcc
	v_mul_lo_u32 v4, v2, v1
	v_add_u32_e32 v4, v4, v2
	v_add_u32_e32 v3, 1, v5
	v_readfirstlane_b32 s10, v1
	v_cmp_ne_u32_e32 vcc, v3, v4
	s_cbranch_vccnz .Lgb5_poll
	buffer_wbl2 sc1
	s_add_i32 s11, s10, 1
	v_mov_b32_e32 v0, s14
	v_mov_b32_e32 v1, s11
	v_add_u32_e32 v0, 0x3800, v0
	s_waitcnt vmcnt(0)
	global_store_dword v0, v1, s[4:5] sc1

; #define LBAR() do { asm volatile("s_waitcnt lgkmcnt(0)" ::: "memory"); __builtin_amdgcn_s_barrier(); asm volatile("" ::: "memory"); } while (0)
; DI KA get_ka() { KA p = (KA)__builtin_amdgcn_kernarg_segment_ptr(); asm volatile("" : "+s"(p)); return p; }
; DI unsigned xb_ld(unsigned* p)              { return __hip_atomic_load(p, __ATOMIC_RELAXED, __HIP_MEMORY_SCOPE_AGENT); }
; #define XB_SPIN(cond, bar) do { unsigned _sp = 0; while (cond) { \
;     if ((++_sp & 255u) == 0u) { if (xb_ld(&(bar)[XB_TMO])) break; if (_sp > XB_SPIN_CAP) { atomicAdd(&(bar)[XB_TMO], 1u); break; } } } } while (0)
; DI void xcd_barrier(const XcdBarrier& b) {
;     ...
;             XB_SPIN(xb_ld(&bar[XB_XGEN(b.x)]) == gen, bar);
;             __builtin_amdgcn_fence(__ATOMIC_ACQUIRE, "agent");
;             asm volatile("s_waitcnt vmcnt(0)" ::: "memory");
;         }
;     }
;     __syncthreads();
; }
; __global__ void __launch_bounds__(512, 2) hymba_fwd(Args a_unused) {
;     ...
;         for (int it = blockIdx.x; it < NUNIT + 2 * NUNIT; it += gridDim.x) {
;             if (it < NUNIT) { lru_unit<true>(get_ka(), l, it, lds); LBAR(); }
;             else { for (int rep = 0; rep < REP_M3G; ++rep) gla_unit<true>(get_ka(), l, it - NUNIT, lds); }
.LBB0_739:
.LBB0_740:
.LBB0_743:
.LBB0_744:
.LBB0_746:
.LBB0_747:
.LBB0_750:
.LBB0_751:
.LBB0_752:
.LBB0_754:
.LBB0_757:
.LBB0_758:
.LBB0_760:
.LBB0_761:
.LBB0_763:
.LBB0_764:
.LBB0_767:
.LBB0_768:
.LBB0_771:
.LBB0_774:
.LBB0_775:
.LBB0_777:
.LBB0_778:
.LBB0_780:
.LBB0_781:
.LBB0_782:
.LBB0_783:
.LBB0_785:
.LBB0_787:
.LBB0_788:
	s_or_b64 exec, exec, s[2:3]
	v_readlane_b32 s2, v254, 20
	v_readlane_b32 s3, v254, 21
	s_andn2_b64 vcc, exec, s[2:3]
	s_waitcnt lgkmcnt(0)
	s_barrier
	s_cbranch_vccnz .LBB0_1057
	s_lshl_b32 s0, s44, 4
	v_writelane_b32 v255, s0, 7
	s_or_b32 s0, s0, 8
	v_writelane_b32 v255, s0, 8
	s_lshl_b32 s0, s44, 11
	s_lshl_b32 s2, s44, 3
	v_writelane_b32 v255, s2, 9
	s_lshl_b64 s[2:3], s[0:1], 2
	v_writelane_b32 v255, s2, 10
	s_lshl_b32 s60, s44, 7
	s_mov_b32 s61, s1
	v_writelane_b32 v255, s3, 11
	s_add_i32 s33, s44, 1
	v_readlane_b32 s0, v254, 0
	v_writelane_b32 v255, s60, 12
	v_mov_b32_e32 v198, s33
	s_mov_b32 s62, s0
	v_writelane_b32 v255, s61, 13
	s_branch .LBB0_792

; DI unsigned xb_ld(unsigned* p)              { return __hip_atomic_load(p, __ATOMIC_RELAXED, __HIP_MEMORY_SCOPE_AGENT); }
; DI unsigned xb_add(unsigned* p, unsigned v) { return __hip_atomic_fetch_add(p, v, __ATOMIC_RELAXED, __HIP_MEMORY_SCOPE_AGENT); }
; #define XB_SPIN(cond, bar) do { unsigned _sp = 0; while (cond) { \
;     if ((++_sp & 255u) == 0u) { if (xb_ld(&(bar)[XB_TMO])) break; if (_sp > XB_SPIN_CAP) { atomicAdd(&(bar)[XB_TMO], 1u); break; } } } } while (0)
; DI void xcd_barrier(const XcdBarrier& b) {
;     asm volatile("s_waitcnt vmcnt(0)" ::: "memory");
;     __syncthreads();
;     if (threadIdx.x == 0) {
;         unsigned* bar = b.bar;
;         __builtin_amdgcn_s_waitcnt(0);
;         unsigned nloc = b.st[0], nx = b.st[1];
;         if (nloc == 0u) { xcd_barrier_complete(bar, b.x, nloc, nx); b.st[0] = nloc; b.st[1] = nx; }
;         const unsigned old = xb_add(&bar[XB_XSUB(b.x)], 1u);
;         const unsigned gen = old / nloc;
;         if (old + 1u == (gen + 1u) * nloc) {
;             __builtin_amdgcn_fence(__ATOMIC_RELEASE, "agent");
;             asm volatile("s_waitcnt vmcnt(0)" ::: "memory");
;             const unsigned og = xb_add(&bar[XB_TOP], 1u);
;             const unsigned tg = og / nx;
;             if (og + 1u == (tg + 1u) * nx) xb_add(&bar[XB_TOPGEN], 1u);
;             else XB_SPIN(xb_ld(&bar[XB_TOPGEN]) == tg, bar);
;             __builtin_amdgcn_fence(__ATOMIC_ACQUIRE, "agent");
;             xb_add(&bar[XB_XGEN(b.x)], 1u);
;             asm volatile("s_waitcnt vmcnt(0)" ::: "memory");
;         } else {
;             XB_SPIN(xb_ld(&bar[XB_XGEN(b.x)]) == gen, bar);
;             __builtin_amdgcn_fence(__ATOMIC_ACQUIRE, "agent");
;             asm volatile("s_waitcnt vmcnt(0)" ::: "memory");
;         }
;     }
;     __syncthreads();
; }
.LBB0_1057:
	v_readlane_b32 s4, v254, 4
	v_readlane_b32 s5, v254, 5
	s_getreg_b32 s0, hwreg(HW_REG_XCC_ID, 0, 4)
	s_waitcnt vmcnt(0)
	s_waitcnt lgkmcnt(0)
	s_barrier
	s_mov_b64 s[2:3], exec
	v_readlane_b32 s6, v254, 1
	v_readlane_b32 s7, v254, 2
	s_and_b64 s[6:7], s[2:3], s[6:7]
	s_mov_b64 exec, s[6:7]
	s_cbranch_execz .LBB0_1109
	s_load_dwordx2 s[4:5], s[4:5], 0xd8
	v_mov_b32_e32 v0, 0x23f00
	ds_read_b32 v2, v0
	s_and_b32 s0, s0, 15
	s_lshl_b32 s12, s0, 8
	s_lshl_b32 s14, s0, 2
	v_mov_b32_e32 v3, 1
	v_mov_b32_e32 v1, 0x1000
	s_waitcnt lgkmcnt(0)
	s_add_u32 s6, s4, s12
	s_addc_u32 s7, s5, 0
	global_atomic_add v3, v1, v3, s[6:7] offset:1024 sc0
	v_cvt_f32_u32_e32 v4, v2
	v_sub_u32_e32 v0, 0, v2
	v_rcp_iflag_f32_e32 v4, v4
	s_waitcnt vmcnt(0)
	v_mov_b32_e32 v5, v3
	v_mul_f32_e32 v4, 0x4f7ffffe, v4
	v_cvt_u32_f32_e32 v4, v4
	v_mul_lo_u32 v1, v0, v4
	v_mul_hi_u32 v1, v4, v1
	v_add_u32_e32 v1, v4, v1
	v_mul_hi_u32 v1, v5, v1
	v_mul_lo_u32 v3, v1, v2
	v_sub_u32_e32 v3, v5, v3
	v_add_u32_e32 v4, 1, v1
	v_cmp_ge_u32_e32 vcc, v3, v2
	s_nop 1
	v_cndmask_b32_e32 v1, v1, v4, vcc
	v_sub_u32_e32 v4, v3, v2
	v_cndmask_b32_e32 v3, v3, v4, vcc
	v_add_u32_e32 v4, 1, v1
	v_cmp_ge_u32_e32 vcc, v3, v2
	s_nop 1
	v_cndmask_b32_e32 v1, v1, v4, vcc
	v_mul_lo_u32 v4, v2, v1
	v_add_u32_e32 v4, v4, v2
	v_add_u32_e32 v3, 1, v5
	v_readfirstlane_b32 s10, v1
	v_cmp_ne_u32_e32 vcc, v3, v4
	s_cbranch_vccnz .Lgb6_poll
	buffer_wbl2 sc1
	s_add_i32 s11, s10, 1
	v_mov_b32_e32 v0, s14
	v_mov_b32_e32 v1, s11
	v_add_u32_e32 v0, 0x3800, v0
	s_waitcnt vmcnt(0)
	global_store_dword v0, v1, s[4:5] sc1

; #define LAS __attribute__((address_space(3)))
; DI KA get_ka() { KA p = (KA)__builtin_amdgcn_kernarg_segment_ptr(); asm volatile("" : "+s"(p)); return p; }
; DI void run_gemm_res(LAS unsigned char* lds, size_t offA, size_t offB, int K, int ssi, float sc, size_t part_off, unsigned epoch) {
;     const KA a = get_ka(); unsigned char* ws = a->ws;
;     pg8::Gemm g{(const bf16_t*)(ws + offA), (const bf16_t*)(ws + offB), MPAD, DM, K};
;     const pg8::EpiRes E = pg8::EpiRes::make(ws, ssi, sc, part_off, epoch);
;     const int G = gridDim.x, bx = blockIdx.x;
;     if ((G & 7) == 0 && (long)276 * (K / 128) >= (long)G * (K / 128)) {
;         pg8::SKOrder S; S.init(K, G, (bx & 7) * (G >> 3) + (bx >> 3));
;         pg8::gemm_phase<pg8::EpiRes, pg8::SKOrder, true, true>(lds, g, S, E);
.LBB0_1060:
.LBB0_1061:
.LBB0_1064:
.LBB0_1065:
.LBB0_1067:
.LBB0_1068:
.LBB0_1071:
.LBB0_1072:
.LBB0_1073:
.LBB0_1075:
.LBB0_1078:
.LBB0_1079:
.LBB0_1081:
.LBB0_1082:
.LBB0_1084:
.LBB0_1085:
.LBB0_1088:
.LBB0_1089:
.LBB0_1092:
.LBB0_1095:
.LBB0_1096:
.LBB0_1098:
.LBB0_1099:
.LBB0_1101:
.LBB0_1102:
.LBB0_1103:
.LBB0_1104:
.LBB0_1106:
.LBB0_1108:
.LBB0_1109:
	s_or_b64 exec, exec, s[2:3]
	v_readlane_b32 s2, v254, 4
	v_readlane_b32 s3, v254, 5
	s_waitcnt lgkmcnt(0)
	s_barrier
	s_load_dwordx2 s[14:15], s[2:3], 0xd8
	v_readlane_b32 s0, v255, 6
	s_add_i32 s33, s0, 2
	s_mul_i32 s0, s33, 0x4500
	s_waitcnt lgkmcnt(0)
	s_add_u32 s44, s14, 0xaf00000
	s_addc_u32 s45, s15, 0
	s_add_u32 s46, s14, 0x1a00000
	s_addc_u32 s47, s15, 0
	s_add_u32 s36, s14, 0x2d00000
	s_addc_u32 s37, s15, 0
	s_lshl_b64 s[2:3], s[0:1], 2
	s_add_u32 s0, s14, s2
	s_addc_u32 s2, s15, s3
	s_add_u32 s4, s0, 0x100000
	s_addc_u32 s5, s2, 0
	v_readlane_b32 s2, v254, 10
	v_readlane_b32 s3, v254, 11
	s_andn2_b64 vcc, exec, s[2:3]
	s_nop 0
	v_cndmask_b32_e64 v0, 0, 1, s[2:3]
	v_cmp_ne_u32_e64 s[8:9], 1, v0
	s_mov_b64 s[2:3], -1
	s_cbranch_vccnz .LBB0_1189
	v_readlane_b32 s6, v254, 12
	v_readlane_b32 s22, v254, 27
	v_readlane_b32 s7, v254, 13
	v_readlane_b32 s23, v254, 28
	s_or_b64 s[2:3], s[22:23], s[6:7]
	s_mov_b32 s2, s1
	s_cmp_lg_u64 s[2:3], 0
	s_cbranch_scc0 .LBB0_1239
	s_ashr_i32 s2, s7, 31
	s_add_u32 s6, s6, s2
	s_mov_b32 s3, s2
	s_addc_u32 s7, s7, s2
	s_xor_b64 s[6:7], s[6:7], s[2:3]
	v_cvt_f32_u32_e32 v0, s6
	v_cvt_f32_u32_e32 v1, s7
	s_sub_u32 s0, 0, s6
	s_subb_u32 s12, 0, s7
	v_fmac_f32_e32 v0, 0x4f800000, v1
	v_rcp_f32_e32 v0, v0
	s_nop 0
	v_mul_f32_e32 v0, 0x5f7ffffc, v0
	v_mul_f32_e32 v1, 0x2f800000, v0
	v_trunc_f32_e32 v1, v1
	v_fmac_f32_e32 v0, 0xcf800000, v1
	v_cvt_u32_f32_e32 v1, v1
	v_cvt_u32_f32_e32 v0, v0
	v_readfirstlane_b32 s13, v1
	v_readfirstlane_b32 s10, v0
	s_mul_i32 s11, s0, s13
	s_mul_hi_u32 s17, s0, s10
	s_mul_i32 s16, s12, s10
	s_add_i32 s11, s17, s11
	s_add_i32 s11, s11, s16
	s_mul_i32 s18, s0, s10
	s_mul_i32 s17, s10, s11
	s_mul_hi_u32 s19, s10, s18
	s_mul_hi_u32 s16, s10, s11
	s_add_u32 s17, s19, s17
	s_addc_u32 s16, 0, s16
	s_mul_hi_u32 s20, s13, s18
	s_mul_i32 s18, s13, s18
	s_add_u32 s17, s17, s18
	s_mul_hi_u32 s19, s13, s11
	s_addc_u32 s16, s16, s20
	s_addc_u32 s17, s19, 0
	s_mul_i32 s11, s13, s11
	s_add_u32 s11, s16, s11
	s_addc_u32 s16, 0, s17
	s_add_u32 s17, s10, s11
	s_cselect_b64 s[10:11], -1, 0
	s_cmp_lg_u64 s[10:11], 0
	s_addc_u32 s13, s13, s16
	s_mul_i32 s10, s0, s13
	s_mul_hi_u32 s11, s0, s17
	s_add_i32 s10, s11, s10
	s_mul_i32 s12, s12, s17
	s_add_i32 s10, s10, s12
	s_mul_i32 s0, s0, s17
	s_mul_hi_u32 s12, s13, s0
	s_mul_i32 s16, s13, s0
	s_mul_i32 s19, s17, s10
	s_mul_hi_u32 s0, s17, s0
	s_mul_hi_u32 s18, s17, s10
	s_add_u32 s0, s0, s19
	s_addc_u32 s18, 0, s18
	s_add_u32 s0, s0, s16
	s_mul_hi_u32 s11, s13, s10
	s_addc_u32 s0, s18, s12
	s_addc_u32 s11, s11, 0
	s_mul_i32 s10, s13, s10
	s_add_u32 s0, s0, s10
	s_addc_u32 s12, 0, s11
	s_add_u32 s0, s17, s0
	s_cselect_b64 s[10:11], -1, 0
	s_cmp_lg_u64 s[10:11], 0
	s_addc_u32 s16, s13, s12
	s_ashr_i32 s10, s23, 31
	s_add_u32 s12, s22, s10
	s_mov_b32 s11, s10
	s_addc_u32 s13, s23, s10
	s_xor_b64 s[12:13], s[12:13], s[10:11]
	s_mul_i32 s18, s12, s16
	s_mul_hi_u32 s19, s12, s0
	s_mul_hi_u32 s17, s12, s16
	s_add_u32 s18, s19, s18
	s_addc_u32 s17, 0, s17
	s_mul_hi_u32 s20, s13, s0
	s_mul_i32 s0, s13, s0
	s_add_u32 s0, s18, s0
	s_mul_hi_u32 s19, s13, s16
	s_addc_u32 s0, s17, s20
	s_addc_u32 s17, s19, 0
	s_mul_i32 s16, s13, s16
	s_add_u32 s0, s0, s16
	s_addc_u32 s20, 0, s17
	s_mul_i32 s16, s6, s20
	s_mul_hi_u32 s17, s6, s0
	s_add_i32 s16, s17, s16
	s_mul_i32 s17, s7, s0
	s_add_i32 s21, s16, s17
	s_sub_i32 s18, s13, s21
	s_mul_i32 s16, s6, s0
	s_sub_u32 s12, s12, s16
	s_cselect_b64 s[16:17], -1, 0
	s_cmp_lg_u64 s[16:17], 0
	s_subb_u32 s22, s18, s7
	s_sub_u32 s23, s12, s6
	s_cselect_b64 s[18:19], -1, 0
	s_cmp_lg_u64 s[18:19], 0
	s_subb_u32 s18, s22, 0
	s_cmp_ge_u32 s18, s7
	s_cselect_b32 s19, -1, 0
	s_cmp_ge_u32 s23, s6
	s_cselect_b32 s22, -1, 0
	s_cmp_eq_u32 s18, s7
	s_cselect_b32 s18, s22, s19
	s_add_u32 s19, s0, 1
	s_addc_u32 s22, s20, 0
	s_add_u32 s23, s0, 2
	s_addc_u32 s24, s20, 0
	s_cmp_lg_u32 s18, 0
	s_cselect_b32 s18, s23, s19
	s_cselect_b32 s19, s24, s22
	s_cmp_lg_u64 s[16:17], 0
	s_subb_u32 s13, s13, s21
	s_cmp_ge_u32 s13, s7
	s_cselect_b32 s16, -1, 0
	s_cmp_ge_u32 s12, s6
	s_cselect_b32 s6, -1, 0
	s_cmp_eq_u32 s13, s7
	s_cselect_b32 s6, s6, s16
	s_cmp_lg_u32 s6, 0
	s_cselect_b32 s7, s19, s20
	s_cselect_b32 s6, s18, s0
	s_xor_b64 s[2:3], s[10:11], s[2:3]
	s_xor_b64 s[6:7], s[6:7], s[2:3]
	s_sub_u32 s2, s6, s2
	s_cbranch_execnz .LBB0_1113

; #define PG8_WAIT_V(n) asm volatile("s_waitcnt vmcnt(" #n ")" ::: "memory")
; #define PG8_BAR __builtin_amdgcn_s_barrier()
; template <class Epi, class Sched, bool ALIGN_EPI = false, bool SP2 = false>
; __device__ __forceinline__ void gemm_phase(PG8_LAS unsigned char* lds, const Gemm g, const Sched& S, const Epi& E) {
;     ...
;     const int tid = tid_, wid = __builtin_amdgcn_readfirstlane(tid >> 6), lane = tid & 63, wr = wid >> 2, wc = wid & 3, fr = lane & 15, fq = lane >> 4;
;     const int K = g.K;
;     unsigned voffA[2], voffB[2];
; #pragma unroll
;     for (int i = 0; i < 2; ++i) { int R, C; stage_rc(tid * 16 + i * 8192, R, C); const int Rb = Epi::PERM ? ((R & ~31) + perm32(R & 31)) : R;
;         voffA[i] = (unsigned)(R * K + C) * 2u; voffB[i] = (unsigned)(Rb * K + C) * 2u; }
;     const size_t kstep = (size_t)(BK * 2);
;     const size_t hstep = (size_t)HALF * K * 2;
;     const size_t tstep = 2 * hstep;
;     const unsigned ldsw = (unsigned)wid * 1024u;
;     const int aoff = lds_byte(wr * 64 + fr, fq * 8), boff = lds_byte(wc * 32 + fr, fq * 8);
;     ...
;     Unit cur, nxt; int ui = 0;
;     if (!S.next(0, cur)) return;
;     f32x4 acc[2][2][4][2];
; #pragma unroll
;     for (int a = 0; a < 2; ++a)
; #pragma unroll
;         for (int b = 0; b < 2; ++b)
; #pragma unroll
;             for (int m = 0; m < 4; ++m)
; #pragma unroll
;                 for (int n = 0; n < 2; ++n) acc[a][b][m][n] = (f32x4){0.f, 0.f, 0.f, 0.f};
;     bf16x8 At[4][2], B0[2][2], B1[2][2];
;     const char* cA = (const char*)g.A + (size_t)cur.pm * tstep + (size_t)cur.kt0 * kstep; const char* cB = (const char*)g.Bt + (size_t)cur.pn * tstep + (size_t)cur.kt0 * kstep;
;     S.a_ready(cur);
;     if constexpr (SP2) {
;         PG8_STAGE(PG8_SB(0, 0), cB, voffB); PG8_STAGE(PG8_SB(0, 1), cB + hstep, voffB); PG8_STAGE(PG8_SA(0, 0), cA, voffA); PG8_STAGE(PG8_SA(0, 1), cA + hstep, voffA);
;         if (wr == 1) PG8_BAR;
;         PG8_WAIT_V(2); PG8_BAR;
;         PG8_STAGE(PG8_SB(1, 0), cB + kstep, voffB); PG8_STAGE(PG8_SA(1, 0), cA + kstep, voffA); PG8_STAGE(PG8_SB(1, 1), cB + hstep + kstep, voffB);
;         PG8_WAIT_V(6); PG8_BAR;
;     } else {
;         PG8_STAGE(PG8_SB(0, 0), cB, voffB); PG8_STAGE(PG8_SA(0, 0), cA, voffA); PG8_STAGE(PG8_SB(0, 1), cB + hstep, voffB); PG8_STAGE(PG8_SA(0, 1), cA + hstep, voffA);
;         if (wr == 1) PG8_BAR;
;         PG8_WAIT_V(4); PG8_BAR;
.LBB0_1241:
.LBB0_1244:
.LBB0_1245:
.LBB0_1246:
.LBB0_1248:
.LBB0_1251:
.LBB0_1252:
.LBB0_1254:
.LBB0_1255:
.LBB0_1257:
.LBB0_1258:
.LBB0_1261:
.LBB0_1262:
.LBB0_1265:
.LBB0_1268:
.LBB0_1269:
.LBB0_1271:
.LBB0_1272:
.LBB0_1274:
.LBB0_1275:
.LBB0_1276:
.LBB0_1277:
.LBB0_1279:
.LBB0_1281:
.LBB0_1282:
	s_or_b64 exec, exec, s[2:3]
	v_readlane_b32 s2, v254, 4
	v_readlane_b32 s4, v254, 60
	v_readlane_b32 s3, v254, 5
	v_mov_b32_e32 v8, v212
	v_readlane_b32 s5, v254, 61
	s_waitcnt lgkmcnt(0)
	s_barrier
	s_and_b64 vcc, exec, s[4:5]
	v_readfirstlane_b32 s12, v8
	s_cbranch_vccnz .LBB0_1302
	v_lshlrev_b32_e32 v0, 4, v8
	v_add_u32_e32 v1, 0x2000, v0
	v_ashrrev_i32_e32 v2, 31, v1
	v_lshrrev_b32_e32 v2, 22, v2
	v_add_u32_e32 v2, v1, v2
	v_ashrrev_i32_e32 v9, 10, v2
	v_mul_i32_i24_e32 v2, 0x400, v9
	v_sub_u32_e32 v1, v1, v2
	v_lshrrev_b32_e32 v2, 4, v1
	v_bitop3_b32 v1, v2, v1, 32 bitop3:0x6c
	v_ashrrev_i32_e32 v2, 31, v1
	v_lshrrev_b32_e32 v2, 26, v2
	v_add_u32_e32 v2, v1, v2
	v_lshlrev_b32_e32 v3, 3, v9
	v_ashrrev_i32_e32 v10, 6, v2
	v_and_b32_e32 v3, -16, v3
	v_add_u32_e32 v3, v10, v3
	s_load_dwordx2 s[6:7], s[2:3], 0xd8
	v_and_b32_e32 v4, 3, v10
	s_mov_b32 s2, 0x1fffe0
	v_lshrrev_b32_e32 v5, 2, v3
	v_lshlrev_b32_e32 v6, 1, v3
	v_and_b32_e32 v2, 0xc0, v2
	v_and_or_b32 v4, v3, s2, v4
	v_and_b32_e32 v5, 4, v5
	v_and_b32_e32 v6, 24, v6
	v_sub_u32_e32 v1, v1, v2
	v_or3_b32 v4, v4, v5, v6
	v_lshlrev_b32_e32 v5, 5, v9
	v_ashrrev_i16_sdwa v1, v216, sext(v1) dst_sel:DWORD dst_unused:UNUSED_PAD src0_sel:DWORD src1_sel:BYTE_0
	v_and_b32_e32 v5, 32, v5
	v_bfe_i32 v11, v1, 0, 16
	v_add_lshl_u32 v1, v5, v11, 1
	v_lshl_add_u32 v128, v4, 11, v1
	v_lshl_add_u32 v130, v3, 11, v1
	v_bfe_i32 v1, v8, 27, 1
	v_lshrrev_b32_e32 v1, 22, v1
	v_add_u32_e32 v1, v0, v1
	v_and_b32_e32 v1, 0xfffffc00, v1
	v_sub_u32_e32 v0, v0, v1
	v_lshrrev_b32_e32 v1, 4, v0
	v_ashrrev_i32_e32 v2, 31, v8
	v_bitop3_b32 v0, v1, v0, 32 bitop3:0x6c
	v_lshrrev_b32_e32 v2, 26, v2
	v_ashrrev_i32_e32 v1, 31, v0
	v_add_u32_e32 v2, v8, v2
	v_lshrrev_b32_e32 v1, 26, v1
	v_ashrrev_i32_e32 v13, 6, v2
	v_add_u32_e32 v1, v0, v1
	v_lshlrev_b32_e32 v2, 3, v13
	s_waitcnt lgkmcnt(0)
	s_add_u32 s0, s6, 0x2d00000
	v_ashrrev_i32_e32 v12, 6, v1
	v_and_b32_e32 v2, -16, v2
	s_addc_u32 s28, s7, 0
	v_add_u32_e32 v2, v12, v2
	s_add_u32 s29, s6, 0x1c00000
	v_and_b32_e32 v3, 3, v12
	v_lshrrev_b32_e32 v4, 2, v2
	v_lshlrev_b32_e32 v5, 1, v2
	v_and_b32_e32 v1, 0xc0, v1
	s_addc_u32 s30, s7, 0
	s_ashr_i32 s14, s12, 6
	v_and_or_b32 v3, v2, s2, v3
	v_and_b32_e32 v4, 4, v4
	v_and_b32_e32 v5, 24, v5
	v_sub_u32_e32 v0, v0, v1
	s_ashr_i32 s13, s12, 8
	s_lshl_b32 s31, s14, 10
	v_or3_b32 v3, v3, v4, v5
	v_lshlrev_b32_e32 v4, 5, v13
	v_ashrrev_i16_sdwa v0, v216, sext(v0) dst_sel:DWORD dst_unused:UNUSED_PAD src0_sel:DWORD src1_sel:BYTE_0
	v_readlane_b32 s2, v254, 36
	v_and_b32_e32 v4, 32, v4
	v_bfe_i32 v14, v0, 0, 16
	v_readlane_b32 s3, v254, 37
	s_add_u32 s22, s29, s2
	v_add_lshl_u32 v0, v4, v14, 1
	s_addc_u32 s23, s30, s3
	s_add_i32 s34, s31, 0
	v_lshl_add_u32 v144, v3, 11, v0
	s_add_i32 m0, s34, 0x10000
	v_lshl_add_u32 v132, v2, 11, v0
	global_load_lds_dwordx4 v144, s[22:23]
	s_add_i32 m0, s34, 0x12000
	s_add_u32 s2, s22, 0x40000
	global_load_lds_dwordx4 v128, s[22:23]
	s_addc_u32 s3, s23, 0
	s_add_i32 m0, s34, 0x14000
	v_mov_b32_e32 v129, v145
	global_load_lds_dwordx4 v144, s[2:3]
	s_add_i32 m0, s34, 0x16000
	v_mov_b32_e32 v133, v145
	global_load_lds_dwordx4 v128, s[2:3]
	v_readlane_b32 s2, v254, 34
	v_readlane_b32 s3, v254, 35
	s_add_u32 s24, s0, s2
	s_addc_u32 s25, s28, s3
	s_add_i32 s35, s34, 0x2000
	s_mov_b32 m0, s34
	s_add_u32 s2, s24, 0x40000
	global_load_lds_dwordx4 v132, s[24:25]
	s_mov_b32 m0, s35
	s_addc_u32 s3, s25, 0
	s_add_i32 s36, s34, 0x4000
	global_load_lds_dwordx4 v130, s[24:25]
	s_mov_b32 m0, s36
	s_add_i32 s37, s34, 0x6000
	global_load_lds_dwordx4 v132, s[2:3]
	s_mov_b32 m0, s37
	v_mov_b32_e32 v131, v145
	global_load_lds_dwordx4 v130, s[2:3]
	s_cmp_eq_u32 s13, 1
	v_lshl_add_u64 v[6:7], s[22:23], 0, v[144:145]
	v_lshl_add_u64 v[4:5], s[22:23], 0, v[128:129]
	v_lshl_add_u64 v[0:1], s[24:25], 0, v[132:133]
	s_cselect_b64 s[2:3], -1, 0
	s_cmp_lg_u32 s13, 1
	v_lshl_add_u64 v[2:3], s[24:25], 0, v[130:131]
	s_cbranch_scc1 .LBB0_1285
	s_barrier

; #define LAS __attribute__((address_space(3)))
; DI KA get_ka() { KA p = (KA)__builtin_amdgcn_kernarg_segment_ptr(); asm volatile("" : "+s"(p)); return p; }
; DI void run_gemm_res(LAS unsigned char* lds, size_t offA, size_t offB, int K, int ssi, float sc, size_t part_off, unsigned epoch) {
;     const KA a = get_ka(); unsigned char* ws = a->ws;
;     pg8::Gemm g{(const bf16_t*)(ws + offA), (const bf16_t*)(ws + offB), MPAD, DM, K};
;     const pg8::EpiRes E = pg8::EpiRes::make(ws, ssi, sc, part_off, epoch);
;     const int G = gridDim.x, bx = blockIdx.x;
;     if ((G & 7) == 0 && (long)276 * (K / 128) >= (long)G * (K / 128)) {
;         pg8::SKOrder S; S.init(K, G, (bx & 7) * (G >> 3) + (bx >> 3));
;         pg8::gemm_phase<pg8::EpiRes, pg8::SKOrder, true, true>(lds, g, S, E);
.LBB0_1305:
.LBB0_1306:
.LBB0_1309:
.LBB0_1310:
.LBB0_1312:
.LBB0_1313:
.LBB0_1316:
.LBB0_1317:
.LBB0_1318:
.LBB0_1320:
.LBB0_1323:
.LBB0_1324:
.LBB0_1326:
.LBB0_1327:
.LBB0_1329:
.LBB0_1330:
.LBB0_1333:
.LBB0_1334:
.LBB0_1337:
.LBB0_1340:
.LBB0_1341:
.LBB0_1343:
.LBB0_1344:
.LBB0_1346:
.LBB0_1347:
.LBB0_1348:
.LBB0_1349:
.LBB0_1351:
.LBB0_1353:
.LBB0_1354:
	s_or_b64 exec, exec, s[2:3]
	v_readlane_b32 s2, v254, 4
	v_readlane_b32 s3, v254, 5
	s_waitcnt lgkmcnt(0)
	s_barrier
	s_load_dwordx2 s[10:11], s[2:3], 0xd8
	v_readlane_b32 s0, v255, 6
	s_add_i32 s41, s0, 3
	s_mul_i32 s0, s41, 0x4500
	s_waitcnt lgkmcnt(0)
	s_add_u32 s33, s10, 0x5000000
	s_addc_u32 s38, s11, 0
	s_add_u32 s39, s10, 0x2700000
	s_addc_u32 s40, s11, 0
	s_add_u32 s28, s10, 0x2d00000
	s_addc_u32 s29, s11, 0
	s_lshl_b64 s[2:3], s[0:1], 2
	s_add_u32 s0, s10, s2
	s_addc_u32 s2, s11, s3
	s_add_u32 s14, s0, 0x100000
	s_addc_u32 s15, s2, 0
	s_and_b64 vcc, exec, s[8:9]
	s_mov_b64 s[2:3], -1
	s_cbranch_vccnz .LBB0_1434
	v_readlane_b32 s4, v254, 12
	v_readlane_b32 s20, v254, 22
	v_readlane_b32 s5, v254, 13
	v_readlane_b32 s21, v254, 23
	s_or_b64 s[2:3], s[20:21], s[4:5]
	s_mov_b32 s2, s1
	s_cmp_lg_u64 s[2:3], 0
	s_cbranch_scc0 .LBB0_1488
	s_ashr_i32 s2, s5, 31
	s_add_u32 s4, s4, s2
	s_mov_b32 s3, s2
	s_addc_u32 s5, s5, s2
	s_xor_b64 s[4:5], s[4:5], s[2:3]
	v_cvt_f32_u32_e32 v0, s4
	v_cvt_f32_u32_e32 v1, s5
	s_sub_u32 s0, 0, s4
	s_subb_u32 s8, 0, s5
	v_fmac_f32_e32 v0, 0x4f800000, v1
	v_rcp_f32_e32 v0, v0
	s_nop 0
	v_mul_f32_e32 v0, 0x5f7ffffc, v0
	v_mul_f32_e32 v1, 0x2f800000, v0
	v_trunc_f32_e32 v1, v1
	v_fmac_f32_e32 v0, 0xcf800000, v1
	v_cvt_u32_f32_e32 v1, v1
	v_cvt_u32_f32_e32 v0, v0
	v_readfirstlane_b32 s9, v1
	v_readfirstlane_b32 s6, v0
	s_mul_i32 s7, s0, s9
	s_mul_hi_u32 s13, s0, s6
	s_mul_i32 s12, s8, s6
	s_add_i32 s7, s13, s7
	s_add_i32 s7, s7, s12
	s_mul_i32 s16, s0, s6
	s_mul_i32 s13, s6, s7
	s_mul_hi_u32 s17, s6, s16
	s_mul_hi_u32 s12, s6, s7
	s_add_u32 s13, s17, s13
	s_addc_u32 s12, 0, s12
	s_mul_hi_u32 s18, s9, s16
	s_mul_i32 s16, s9, s16
	s_add_u32 s13, s13, s16
	s_mul_hi_u32 s17, s9, s7
	s_addc_u32 s12, s12, s18
	s_addc_u32 s13, s17, 0
	s_mul_i32 s7, s9, s7
	s_add_u32 s7, s12, s7
	s_addc_u32 s12, 0, s13
	s_add_u32 s13, s6, s7
	s_cselect_b64 s[6:7], -1, 0
	s_cmp_lg_u64 s[6:7], 0
	s_addc_u32 s9, s9, s12
	s_mul_i32 s6, s0, s9
	s_mul_hi_u32 s7, s0, s13
	s_add_i32 s6, s7, s6
	s_mul_i32 s8, s8, s13
	s_add_i32 s6, s6, s8
	s_mul_i32 s0, s0, s13
	s_mul_hi_u32 s8, s9, s0
	s_mul_i32 s12, s9, s0
	s_mul_i32 s17, s13, s6
	s_mul_hi_u32 s0, s13, s0
	s_mul_hi_u32 s16, s13, s6
	s_add_u32 s0, s0, s17
	s_addc_u32 s16, 0, s16
	s_add_u32 s0, s0, s12
	s_mul_hi_u32 s7, s9, s6
	s_addc_u32 s0, s16, s8
	s_addc_u32 s7, s7, 0
	s_mul_i32 s6, s9, s6
	s_add_u32 s0, s0, s6
	s_addc_u32 s8, 0, s7
	s_add_u32 s0, s13, s0
	s_cselect_b64 s[6:7], -1, 0
	s_cmp_lg_u64 s[6:7], 0
	s_addc_u32 s12, s9, s8
	s_ashr_i32 s6, s21, 31
	s_add_u32 s8, s20, s6
	s_mov_b32 s7, s6
	s_addc_u32 s9, s21, s6
	s_xor_b64 s[8:9], s[8:9], s[6:7]
	s_mul_i32 s16, s8, s12
	s_mul_hi_u32 s17, s8, s0
	s_mul_hi_u32 s13, s8, s12
	s_add_u32 s16, s17, s16
	s_addc_u32 s13, 0, s13
	s_mul_hi_u32 s18, s9, s0
	s_mul_i32 s0, s9, s0
	s_add_u32 s0, s16, s0
	s_mul_hi_u32 s17, s9, s12
	s_addc_u32 s0, s13, s18
	s_addc_u32 s13, s17, 0
	s_mul_i32 s12, s9, s12
	s_add_u32 s0, s0, s12
	s_addc_u32 s18, 0, s13
	s_mul_i32 s12, s4, s18
	s_mul_hi_u32 s13, s4, s0
	s_add_i32 s12, s13, s12
	s_mul_i32 s13, s5, s0
	s_add_i32 s19, s12, s13
	s_sub_i32 s16, s9, s19
	s_mul_i32 s12, s4, s0
	s_sub_u32 s8, s8, s12
	s_cselect_b64 s[12:13], -1, 0
	s_cmp_lg_u64 s[12:13], 0
	s_subb_u32 s20, s16, s5
	s_sub_u32 s21, s8, s4
	s_cselect_b64 s[16:17], -1, 0
	s_cmp_lg_u64 s[16:17], 0
	s_subb_u32 s16, s20, 0
	s_cmp_ge_u32 s16, s5
	s_cselect_b32 s17, -1, 0
	s_cmp_ge_u32 s21, s4
	s_cselect_b32 s20, -1, 0
	s_cmp_eq_u32 s16, s5
	s_cselect_b32 s16, s20, s17
	s_add_u32 s17, s0, 1
	s_addc_u32 s20, s18, 0
	s_add_u32 s21, s0, 2
	s_addc_u32 s22, s18, 0
	s_cmp_lg_u32 s16, 0
	s_cselect_b32 s16, s21, s17
	s_cselect_b32 s17, s22, s20
	s_cmp_lg_u64 s[12:13], 0
	s_subb_u32 s9, s9, s19
	s_cmp_ge_u32 s9, s5
	s_cselect_b32 s12, -1, 0
	s_cmp_ge_u32 s8, s4
	s_cselect_b32 s4, -1, 0
	s_cmp_eq_u32 s9, s5
	s_cselect_b32 s4, s4, s12
	s_cmp_lg_u32 s4, 0
	s_cselect_b32 s5, s17, s18
	s_cselect_b32 s4, s16, s0
	s_xor_b64 s[2:3], s[6:7], s[2:3]
	s_xor_b64 s[4:5], s[4:5], s[2:3]
	s_sub_u32 s2, s4, s2
	s_cbranch_execnz .LBB0_1358

; DI unsigned xb_ld(unsigned* p)              { return __hip_atomic_load(p, __ATOMIC_RELAXED, __HIP_MEMORY_SCOPE_AGENT); }
; DI unsigned xb_add(unsigned* p, unsigned v) { return __hip_atomic_fetch_add(p, v, __ATOMIC_RELAXED, __HIP_MEMORY_SCOPE_AGENT); }
; #define XB_SPIN(cond, bar) do { unsigned _sp = 0; while (cond) { \
;     if ((++_sp & 255u) == 0u) { if (xb_ld(&(bar)[XB_TMO])) break; if (_sp > XB_SPIN_CAP) { atomicAdd(&(bar)[XB_TMO], 1u); break; } } } } while (0)
; DI void xcd_barrier(const XcdBarrier& b) {
;     asm volatile("s_waitcnt vmcnt(0)" ::: "memory");
;     __syncthreads();
;     if (threadIdx.x == 0) {
;         unsigned* bar = b.bar;
;         __builtin_amdgcn_s_waitcnt(0);
;         unsigned nloc = b.st[0], nx = b.st[1];
;         if (nloc == 0u) { xcd_barrier_complete(bar, b.x, nloc, nx); b.st[0] = nloc; b.st[1] = nx; }
;         const unsigned old = xb_add(&bar[XB_XSUB(b.x)], 1u);
;         const unsigned gen = old / nloc;
;         if (old + 1u == (gen + 1u) * nloc) {
;             __builtin_amdgcn_fence(__ATOMIC_RELEASE, "agent");
;             asm volatile("s_waitcnt vmcnt(0)" ::: "memory");
;             const unsigned og = xb_add(&bar[XB_TOP], 1u);
;             const unsigned tg = og / nx;
;             if (og + 1u == (tg + 1u) * nx) xb_add(&bar[XB_TOPGEN], 1u);
;             else XB_SPIN(xb_ld(&bar[XB_TOPGEN]) == tg, bar);
;             __builtin_amdgcn_fence(__ATOMIC_ACQUIRE, "agent");
;             xb_add(&bar[XB_XGEN(b.x)], 1u);
;             asm volatile("s_waitcnt vmcnt(0)" ::: "memory");
;         } else {
;             XB_SPIN(xb_ld(&bar[XB_XGEN(b.x)]) == gen, bar);
;             __builtin_amdgcn_fence(__ATOMIC_ACQUIRE, "agent");
;             asm volatile("s_waitcnt vmcnt(0)" ::: "memory");
;         }
;     }
;     __syncthreads();
; }
.LBB0_1478:
	s_load_dwordx2 s[4:5], s[4:5], 0xd8
	v_mov_b32_e32 v0, 0x23f00
	ds_read_b32 v2, v0
	s_and_b32 s0, s0, 15
	s_lshl_b32 s12, s0, 8
	s_lshl_b32 s14, s0, 2
	v_mov_b32_e32 v3, 1
	v_mov_b32_e32 v1, 0x1000
	s_waitcnt lgkmcnt(0)
	s_add_u32 s6, s4, s12
	s_addc_u32 s7, s5, 0
	global_atomic_add v3, v1, v3, s[6:7] offset:1024 sc0
	v_cvt_f32_u32_e32 v4, v2
	v_sub_u32_e32 v0, 0, v2
	v_rcp_iflag_f32_e32 v4, v4
	s_waitcnt vmcnt(0)
	v_mov_b32_e32 v5, v3
	v_mul_f32_e32 v4, 0x4f7ffffe, v4
	v_cvt_u32_f32_e32 v4, v4
	v_mul_lo_u32 v1, v0, v4
	v_mul_hi_u32 v1, v4, v1
	v_add_u32_e32 v1, v4, v1
	v_mul_hi_u32 v1, v5, v1
	v_mul_lo_u32 v3, v1, v2
	v_sub_u32_e32 v3, v5, v3
	v_add_u32_e32 v4, 1, v1
	v_cmp_ge_u32_e32 vcc, v3, v2
	s_nop 1
	v_cndmask_b32_e32 v1, v1, v4, vcc
	v_sub_u32_e32 v4, v3, v2
	v_cndmask_b32_e32 v3, v3, v4, vcc
	v_add_u32_e32 v4, 1, v1
	v_cmp_ge_u32_e32 vcc, v3, v2
	s_nop 1
	v_cndmask_b32_e32 v1, v1, v4, vcc
	v_mul_lo_u32 v4, v2, v1
	v_add_u32_e32 v4, v4, v2
	v_add_u32_e32 v3, 1, v5
	v_readfirstlane_b32 s10, v1
	v_cmp_ne_u32_e32 vcc, v3, v4
	s_cbranch_vccnz .Lgb9_poll
	buffer_wbl2 sc1
	s_add_i32 s11, s10, 1
	v_mov_b32_e32 v0, s14
	v_mov_b32_e32 v1, s11
	v_add_u32_e32 v0, 0x3800, v0
	s_waitcnt vmcnt(0)
	global_store_dword v0, v1, s[4:5] sc1

; DI unsigned xb_ld(unsigned* p)              { return __hip_atomic_load(p, __ATOMIC_RELAXED, __HIP_MEMORY_SCOPE_AGENT); }
; #define XB_SPIN(cond, bar) do { unsigned _sp = 0; while (cond) { \
;     if ((++_sp & 255u) == 0u) { if (xb_ld(&(bar)[XB_TMO])) break; if (_sp > XB_SPIN_CAP) { atomicAdd(&(bar)[XB_TMO], 1u); break; } } } } while (0)
; DI void xcd_barrier(const XcdBarrier& b) {
;     ...
;             XB_SPIN(xb_ld(&bar[XB_XGEN(b.x)]) == gen, bar);
;             __builtin_amdgcn_fence(__ATOMIC_ACQUIRE, "agent");
;             asm volatile("s_waitcnt vmcnt(0)" ::: "memory");
;         }
.Lgb9_done:
	buffer_inv sc1
	s_waitcnt vmcnt(0)
	s_mov_b64 s[8:9], 0
	s_branch .Lgb9_tail

; #define GSYNC() do { XcdBarrier _b; _b.bar = (unsigned*)(get_ka()->ws); _b.x = xb_xcc_id(); _b.st = (volatile LAS unsigned*)(lds + 147200); xcd_barrier(_b); } while (0)
; __global__ void __launch_bounds__(512, 2) hymba_fwd(Args a_unused) {
;     ...
;     for (int l = 0; l < 2; ++l) {
;     ...
;         GSYNC();
.LBB0_1490:
.LBB0_1493:
.LBB0_1494:
.LBB0_1495:
.LBB0_1497:
.LBB0_1500:
.LBB0_1501:
.LBB0_1503:
.LBB0_1504:
.LBB0_1506:
.LBB0_1507:
.LBB0_1510:
.LBB0_1511:
.Lpost_getpc3:
.LBB0_1512:
.LBB0_1514:
.LBB0_1517:
.LBB0_1518:
.LBB0_1520:
.LBB0_1521:
.LBB0_1523:
.LBB0_1524:
.LBB0_1525:
.LBB0_1526:
.LBB0_1528:
.Lpost_getpc4:
.LBB0_1529:
.Lgb9_tail:
	s_getpc_b64 s[98:99]
